# scan: static s_setprio 3 for the matrix (triangular-solve) wave
# baseline (speedup 1.0000x reference)
; #define LAS __attribute__((address_space(3)))
; __device__ __forceinline__ void scan_phase2(LAS unsigned char* lds, const int wid, const bf16_t* R, const bf16_t* K, const bf16_t* V, const bf16_t* W, const bf16_t* A,
;                                             const float* k_k, const float* k_a, const float* r_k, bf16_t* Y, float* BON) {
;     ...
;         } else if (wid == 3) {
;             LAS float* MABS = (LAS float*)(lds + L_MAB);
; #pragma unroll 1
;             for (int it = 0; it < NCH + 2; ++it) {
;                 if (it >= 1 && it <= NCH) for (int rp_ = 0; rp_ < 1 + (MK_SC2P & 1); ++rp_) {
.LBB0_1234:
	s_and_b64 vcc, exec, s[54:55]
	s_cbranch_vccz .LBB0_1243
	s_setprio 3
	s_mov_b32 s30, 0
	s_movk_i32 s88, 0xf800
	s_branch .LBB0_1237

; #define LAS __attribute__((address_space(3)))
; __device__ __forceinline__ void scan_phase2(LAS unsigned char* lds, const int wid, const bf16_t* R, const bf16_t* K, const bf16_t* V, const bf16_t* W, const bf16_t* A,
;                                             const float* k_k, const float* k_a, const float* r_k, bf16_t* Y, float* BON) {
;     ...
;         } else if (wid == 3) {
;             LAS float* MABS = (LAS float*)(lds + L_MAB);
; #pragma unroll 1
;             for (int it = 0; it < NCH + 2; ++it) {
.LBB0_1243:
	s_setprio 0
	s_mov_b64 s[54:55], 0

; #define LAS __attribute__((address_space(3)))
; __device__ __forceinline__ void scan_phase2(LAS unsigned char* lds, const int wid, const bf16_t* R, const bf16_t* K, const bf16_t* V, const bf16_t* W, const bf16_t* A,
;                                             const float* k_k, const float* k_a, const float* r_k, bf16_t* Y, float* BON) {
;     ...
;         } else if (wid == 3) {
;             LAS float* MABS = (LAS float*)(lds + L_MAB);
; #pragma unroll 1
;             for (int it = 0; it < NCH + 2; ++it) {
;                 if (it >= 1 && it <= NCH) for (int rp_ = 0; rp_ < 1 + (MK_SC2P & 1); ++rp_) {
.LBB0_2878:
	s_and_b64 vcc, exec, s[54:55]
	s_cbranch_vccz .LBB0_2887
	s_setprio 3
	s_mov_b32 s28, 0
	s_movk_i32 s88, 0xf800
	s_branch .LBB0_2881
